# LN trip: gamma/beta loads of all 4 j-regions issued before the reductions into separate register sets (no vmcnt waits between store regions); 256 VGPRs
# baseline (speedup 1.0000x reference)
; DI float bf_lo(unsigned u) { return __uint_as_float(u << 16); }
; DI float bf_hi(unsigned u) { return __uint_as_float(u & 0xffff0000u); }
; DI void phase_ln(const Params& p, int layer, int gw, int NGW, int lane) {
;     ...
;             float a1 = 0.f, a2 = 0.f;
; #pragma unroll
;             for (int j = 0; j < 4; ++j) { const unsigned yw[4] = {yv[j].x, yv[j].y, yv[j].z, yv[j].w};
; #pragma unroll
;                 for (int e = 0; e < 4; ++e) { const float u0 = v[q][8 * j + 2 * e] * DN_ALPHA + bf_lo(yw[e]), u1 = v[q][8 * j + 2 * e + 1] * DN_ALPHA + bf_hi(yw[e]);
;                     v[q][8 * j + 2 * e] = u0; v[q][8 * j + 2 * e + 1] = u1; a1 += u0 + u1; a2 += u0 * u0 + u1 * u1; } }
;             s1[q] = a1; s2[q] = a2;
.LBB0_363:
	s_waitcnt vmcnt(7)
	v_lshlrev_b32_e32 v136, 16, v30
	v_and_b32_e32 v137, 0xffff0000, v30
	v_pk_fma_f32 v[144:145], v[50:51], s[98:99], v[136:137] op_sel_hi:[1,0,1]
	v_lshlrev_b32_e32 v30, 16, v31
	v_and_b32_e32 v31, 0xffff0000, v31
	v_lshlrev_b32_e32 v50, 16, v32
	v_and_b32_e32 v51, 0xffff0000, v32
	v_pk_fma_f32 v[148:149], v[52:53], s[98:99], v[30:31] op_sel_hi:[1,0,1]
	v_pk_fma_f32 v[146:147], v[42:43], s[98:99], v[50:51] op_sel_hi:[1,0,1]
	s_waitcnt vmcnt(6)
	v_lshlrev_b32_e32 v50, 16, v12
	v_and_b32_e32 v51, 0xffff0000, v12
	v_pk_add_f32 v[162:163], v[144:145], v[144:145] op_sel_hi:[1,0]
	v_pk_mul_f32 v[164:165], v[144:145], v[144:145]
	v_pk_mul_f32 v[30:31], v[148:149], v[148:149]
	v_lshlrev_b32_e32 v32, 16, v33
	v_and_b32_e32 v33, 0xffff0000, v33
	v_pk_fma_f32 v[140:141], v[46:47], s[98:99], v[50:51] op_sel_hi:[1,0,1]
	s_waitcnt vmcnt(5)
	v_lshlrev_b32_e32 v46, 16, v6
	v_and_b32_e32 v47, 0xffff0000, v6
	v_pk_fma_f32 v[150:151], v[44:45], s[98:99], v[32:33] op_sel_hi:[1,0,1]
	v_lshlrev_b32_e32 v44, 16, v10
	v_and_b32_e32 v45, 0xffff0000, v10
	v_lshlrev_b32_e32 v10, 16, v11
	v_and_b32_e32 v11, 0xffff0000, v11
	v_pk_fma_f32 v[46:47], v[58:59], s[98:99], v[46:47] op_sel_hi:[1,0,1]
	v_mov_b32_e32 v162, v164
	v_mov_b32_e32 v0, v165
	v_mov_b32_e32 v58, v31
	v_mov_b32_e32 v59, v149
	v_mov_b32_e32 v31, v148
	v_pk_mul_f32 v[42:43], v[146:147], v[146:147]
	v_pk_fma_f32 v[138:139], v[56:57], s[98:99], v[10:11] op_sel_hi:[1,0,1]
	v_pk_add_f32 v[56:57], v[162:163], v[0:1]
	v_pk_add_f32 v[30:31], v[58:59], v[30:31]
	v_pk_mul_f32 v[32:33], v[150:151], v[150:151]
	v_pk_add_f32 v[30:31], v[30:31], v[56:57]
	v_mov_b32_e32 v56, v43
	v_mov_b32_e32 v57, v147
	v_mov_b32_e32 v43, v146
	v_pk_add_f32 v[42:43], v[56:57], v[42:43]
	v_pk_fma_f32 v[136:137], v[54:55], s[98:99], v[44:45] op_sel_hi:[1,0,1]
	v_pk_add_f32 v[30:31], v[42:43], v[30:31]
	v_mov_b32_e32 v42, v33
	v_mov_b32_e32 v43, v151
	v_mov_b32_e32 v33, v150
	v_pk_mul_f32 v[44:45], v[136:137], v[136:137]
	v_pk_add_f32 v[32:33], v[42:43], v[32:33]
	v_pk_mul_f32 v[10:11], v[138:139], v[138:139]
	v_pk_add_f32 v[30:31], v[32:33], v[30:31]
	v_mov_b32_e32 v32, v45
	v_mov_b32_e32 v33, v137
	v_mov_b32_e32 v45, v136
	v_pk_add_f32 v[32:33], v[32:33], v[44:45]
	v_pk_mul_f32 v[52:53], v[140:141], v[140:141]
	v_pk_add_f32 v[30:31], v[32:33], v[30:31]
	v_mov_b32_e32 v32, v11
	v_mov_b32_e32 v33, v139
	v_mov_b32_e32 v11, v138
	v_lshlrev_b32_e32 v12, 16, v13
	v_and_b32_e32 v13, 0xffff0000, v13
	v_pk_add_f32 v[10:11], v[32:33], v[10:11]
	v_pk_fma_f32 v[142:143], v[48:49], s[98:99], v[12:13] op_sel_hi:[1,0,1]
	v_pk_add_f32 v[10:11], v[10:11], v[30:31]
	v_mov_b32_e32 v30, v53
	v_mov_b32_e32 v31, v141
	v_mov_b32_e32 v53, v140
	v_pk_mul_f32 v[12:13], v[142:143], v[142:143]
	v_pk_add_f32 v[30:31], v[30:31], v[52:53]
	v_pk_mul_f32 v[54:55], v[46:47], v[46:47]
	v_pk_add_f32 v[10:11], v[30:31], v[10:11]
	v_mov_b32_e32 v30, v13
	v_mov_b32_e32 v31, v143
	v_mov_b32_e32 v13, v142
	v_lshlrev_b32_e32 v6, 16, v7
	v_and_b32_e32 v7, 0xffff0000, v7
	v_pk_add_f32 v[12:13], v[30:31], v[12:13]
	v_pk_fma_f32 v[50:51], v[60:61], s[98:99], v[6:7] op_sel_hi:[1,0,1]
	v_pk_add_f32 v[10:11], v[12:13], v[10:11]
	v_mov_b32_e32 v12, v55
	v_mov_b32_e32 v13, v47
	v_mov_b32_e32 v55, v46
	v_pk_mul_f32 v[6:7], v[50:51], v[50:51]
	v_lshlrev_b32_e32 v48, 16, v8
	v_and_b32_e32 v49, 0xffff0000, v8
	v_pk_add_f32 v[12:13], v[12:13], v[54:55]
	v_pk_fma_f32 v[48:49], v[22:23], s[98:99], v[48:49] op_sel_hi:[1,0,1]
	v_pk_add_f32 v[10:11], v[12:13], v[10:11]
	v_mov_b32_e32 v12, v7
	v_mov_b32_e32 v13, v51
	v_mov_b32_e32 v7, v50
	v_pk_mul_f32 v[22:23], v[48:49], v[48:49]
	v_pk_add_f32 v[6:7], v[12:13], v[6:7]
	v_lshlrev_b32_e32 v8, 16, v9
	v_and_b32_e32 v9, 0xffff0000, v9
	v_pk_add_f32 v[6:7], v[6:7], v[10:11]
	v_mov_b32_e32 v10, v23
	v_mov_b32_e32 v11, v49
	v_mov_b32_e32 v23, v48
	v_pk_fma_f32 v[52:53], v[24:25], s[98:99], v[8:9] op_sel_hi:[1,0,1]
	v_pk_add_f32 v[10:11], v[10:11], v[22:23]
	v_pk_mul_f32 v[8:9], v[52:53], v[52:53]
	v_pk_add_f32 v[6:7], v[10:11], v[6:7]
	v_mov_b32_e32 v10, v9
	v_mov_b32_e32 v11, v53
	v_mov_b32_e32 v9, v52
	v_pk_add_f32 v[8:9], v[10:11], v[8:9]
	s_waitcnt vmcnt(4)
	v_lshlrev_b32_e32 v10, 16, v2
	v_and_b32_e32 v11, 0xffff0000, v2
	v_pk_fma_f32 v[30:31], v[14:15], s[98:99], v[10:11] op_sel_hi:[1,0,1]
	v_lshlrev_b32_e32 v2, 16, v3
	v_pk_mul_f32 v[10:11], v[30:31], v[30:31]
	v_and_b32_e32 v3, 0xffff0000, v3
	v_pk_fma_f32 v[42:43], v[16:17], s[98:99], v[2:3] op_sel_hi:[1,0,1]
	v_pk_add_f32 v[6:7], v[8:9], v[6:7]
	v_mov_b32_e32 v8, v11
	v_mov_b32_e32 v9, v31
	v_mov_b32_e32 v11, v30
	v_pk_mul_f32 v[2:3], v[42:43], v[42:43]
	v_lshlrev_b32_e32 v12, 16, v4
	v_and_b32_e32 v13, 0xffff0000, v4
	v_pk_add_f32 v[8:9], v[8:9], v[10:11]
	v_pk_fma_f32 v[32:33], v[18:19], s[98:99], v[12:13] op_sel_hi:[1,0,1]
	v_pk_add_f32 v[6:7], v[8:9], v[6:7]
	v_mov_b32_e32 v8, v3
	v_mov_b32_e32 v9, v43
	v_mov_b32_e32 v3, v42
	v_pk_mul_f32 v[12:13], v[32:33], v[32:33]
	v_lshlrev_b32_e32 v4, 16, v5
	v_and_b32_e32 v5, 0xffff0000, v5
	v_pk_add_f32 v[2:3], v[8:9], v[2:3]
	v_pk_fma_f32 v[44:45], v[20:21], s[98:99], v[4:5] op_sel_hi:[1,0,1]
	v_pk_add_f32 v[2:3], v[2:3], v[6:7]
	v_mov_b32_e32 v6, v13
	v_mov_b32_e32 v7, v33
	v_mov_b32_e32 v13, v32
	v_pk_mul_f32 v[4:5], v[44:45], v[44:45]
	v_pk_add_f32 v[6:7], v[6:7], v[12:13]
	s_waitcnt vmcnt(3)
; DI float bf_lo(unsigned u) { return __uint_as_float(u << 16); }
; DI float bf_hi(unsigned u) { return __uint_as_float(u & 0xffff0000u); }
; DI float shflx(float v, int mask, int lane) { return __int_as_float(__builtin_amdgcn_ds_bpermute((lane ^ mask) << 2, __float_as_int(v))); }
; DI void phase_ln(const Params& p, int layer, int gw, int NGW, int lane) {
;     ...
;             float a1 = 0.f, a2 = 0.f;
; #pragma unroll
;             for (int j = 0; j < 4; ++j) { const unsigned yw[4] = {yv[j].x, yv[j].y, yv[j].z, yv[j].w};
; #pragma unroll
;                 for (int e = 0; e < 4; ++e) { const float u0 = v[q][8 * j + 2 * e] * DN_ALPHA + bf_lo(yw[e]), u1 = v[q][8 * j + 2 * e + 1] * DN_ALPHA + bf_hi(yw[e]);
;                     v[q][8 * j + 2 * e] = u0; v[q][8 * j + 2 * e + 1] = u1; a1 += u0 + u1; a2 += u0 * u0 + u1 * u1; } }
;             s1[q] = a1; s2[q] = a2;
;         }
; #pragma unroll
;         for (int o = 1; o < 64; o <<= 1)
; #pragma unroll
;             for (int q = 0; q < R; ++q) { s1[q] += shflx(s1[q], o, lane); s2[q] += shflx(s2[q], o, lane); }
;         float mean[R], rstd[R];
; #pragma unroll
;         for (int q = 0; q < R; ++q) { mean[q] = s1[q] * (1.f / D); const float var = fmaxf(s2[q] * (1.f / D) - mean[q] * mean[q], 0.f); rstd[q] = 1.0f / sqrtf(var + LN_EPS); }
; #pragma unroll
;         for (int j = 0; j < 4; ++j) {
;             const f32x4 g0 = ((const f32x4*)g)[128 * j + 2 * lane], g1 = ((const f32x4*)g)[128 * j + 2 * lane + 1], b0 = ((const f32x4*)b)[128 * j + 2 * lane], b1 = ((const f32x4*)b)[128 * j + 2 * lane + 1];
	v_lshlrev_b32_e32 v8, 16, v65
	v_pk_add_f32 v[2:3], v[6:7], v[2:3]
	v_mov_b32_e32 v6, v5
	v_mov_b32_e32 v7, v45
	v_mov_b32_e32 v5, v44
	v_pk_add_f32 v[4:5], v[6:7], v[4:5]
	v_lshlrev_b32_e32 v6, 16, v64
	v_pk_add_f32 v[18:19], v[4:5], v[2:3]
	v_lshlrev_b32_e32 v2, 16, v62
	v_and_b32_e32 v3, 0xffff0000, v62
	v_pk_fma_f32 v[94:95], v[94:95], s[98:99], v[2:3] op_sel_hi:[1,0,1]
	v_lshlrev_b32_e32 v4, 16, v63
	v_and_b32_e32 v5, 0xffff0000, v63
	v_add_f32_e32 v0, v95, v94
	v_pk_fma_f32 v[96:97], v[96:97], s[98:99], v[4:5] op_sel_hi:[1,0,1]
	v_and_b32_e32 v7, 0xffff0000, v64
	v_add_f32_e32 v0, 0, v0
	v_add_f32_e32 v4, v97, v96
	v_pk_fma_f32 v[82:83], v[82:83], s[98:99], v[6:7] op_sel_hi:[1,0,1]
	v_and_b32_e32 v9, 0xffff0000, v65
	v_add_f32_e32 v0, v4, v0
	v_add_f32_e32 v6, v83, v82
	v_pk_fma_f32 v[84:85], v[84:85], s[98:99], v[8:9] op_sel_hi:[1,0,1]
	s_waitcnt vmcnt(2)
	v_lshlrev_b32_e32 v10, 16, v38
	v_and_b32_e32 v11, 0xffff0000, v38
	v_pk_mul_f32 v[2:3], v[94:95], v[94:95]
	v_pk_mul_f32 v[4:5], v[96:97], v[96:97]
	v_add_f32_e32 v0, v6, v0
	v_add_f32_e32 v8, v85, v84
	v_pk_fma_f32 v[58:59], v[90:91], s[98:99], v[10:11] op_sel_hi:[1,0,1]
	v_lshlrev_b32_e32 v12, 16, v39
	v_and_b32_e32 v13, 0xffff0000, v39
	v_pk_mul_f32 v[6:7], v[82:83], v[82:83]
	v_add_f32_e32 v0, v8, v0
	v_add_f32_e32 v10, v59, v58
	v_pk_fma_f32 v[62:63], v[92:93], s[98:99], v[12:13] op_sel_hi:[1,0,1]
	v_lshlrev_b32_e32 v14, 16, v40
	v_and_b32_e32 v15, 0xffff0000, v40
	v_add_f32_e32 v4, v5, v4
	v_add_f32_e32 v2, v3, v2
	v_pk_mul_f32 v[8:9], v[84:85], v[84:85]
	v_add_f32_e32 v0, v10, v0
	v_add_f32_e32 v12, v63, v62
	v_pk_fma_f32 v[64:65], v[70:71], s[98:99], v[14:15] op_sel_hi:[1,0,1]
	v_lshlrev_b32_e32 v16, 16, v41
	v_and_b32_e32 v17, 0xffff0000, v41
	v_add_f32_e32 v2, v4, v2
	v_add_f32_e32 v3, v7, v6
	v_pk_mul_f32 v[10:11], v[58:59], v[58:59]
	v_add_f32_e32 v0, v12, v0
	v_add_f32_e32 v14, v65, v64
	v_pk_fma_f32 v[70:71], v[72:73], s[98:99], v[16:17] op_sel_hi:[1,0,1]
	s_waitcnt vmcnt(1)
	v_lshlrev_b32_e32 v20, 16, v34
	v_and_b32_e32 v21, 0xffff0000, v34
	v_add_f32_e32 v8, v9, v8
	v_add_f32_e32 v2, v3, v2
	v_pk_mul_f32 v[12:13], v[62:63], v[62:63]
	v_add_f32_e32 v0, v14, v0
	v_add_f32_e32 v16, v71, v70
	v_pk_fma_f32 v[38:39], v[86:87], s[98:99], v[20:21] op_sel_hi:[1,0,1]
	v_lshlrev_b32_e32 v22, 16, v35
	v_and_b32_e32 v23, 0xffff0000, v35
	v_add_f32_e32 v2, v8, v2
	v_add_f32_e32 v3, v11, v10
	v_pk_mul_f32 v[14:15], v[64:65], v[64:65]
	v_add_f32_e32 v0, v16, v0
	v_add_f32_e32 v20, v39, v38
	v_pk_fma_f32 v[40:41], v[88:89], s[98:99], v[22:23] op_sel_hi:[1,0,1]
	v_lshlrev_b32_e32 v24, 16, v36
	v_and_b32_e32 v25, 0xffff0000, v36
	v_add_f32_e32 v2, v3, v2
	v_add_f32_e32 v3, v13, v12
	v_pk_mul_f32 v[16:17], v[70:71], v[70:71]
	v_add_f32_e32 v0, v20, v0
	v_add_f32_e32 v22, v41, v40
	v_pk_fma_f32 v[54:55], v[78:79], s[98:99], v[24:25] op_sel_hi:[1,0,1]
	v_lshlrev_b32_e32 v34, 16, v37
	v_and_b32_e32 v35, 0xffff0000, v37
	v_add_f32_e32 v2, v3, v2
	v_add_f32_e32 v3, v15, v14
	v_pk_mul_f32 v[20:21], v[38:39], v[38:39]
	v_add_f32_e32 v0, v22, v0
	v_add_f32_e32 v24, v55, v54
	v_pk_fma_f32 v[56:57], v[80:81], s[98:99], v[34:35] op_sel_hi:[1,0,1]
	v_add_f32_e32 v2, v3, v2
	v_add_f32_e32 v3, v17, v16
	v_pk_mul_f32 v[22:23], v[40:41], v[40:41]
	v_add_f32_e32 v0, v24, v0
	v_add_f32_e32 v34, v57, v56
	v_add_f32_e32 v2, v3, v2
	v_add_f32_e32 v3, v21, v20
	v_pk_mul_f32 v[24:25], v[54:55], v[54:55]
	v_add_f32_e32 v0, v34, v0
	s_waitcnt vmcnt(0)
	v_lshlrev_b32_e32 v34, 16, v26
	v_and_b32_e32 v35, 0xffff0000, v26
	v_add_f32_e32 v2, v3, v2
	v_add_f32_e32 v3, v23, v22
	v_pk_mul_f32 v[60:61], v[56:57], v[56:57]
	v_pk_fma_f32 v[34:35], v[74:75], s[98:99], v[34:35] op_sel_hi:[1,0,1]
	v_add_f32_e32 v2, v3, v2
	v_add_f32_e32 v3, v25, v24
	v_pk_mul_f32 v[72:73], v[34:35], v[34:35]
	v_add_f32_e32 v2, v3, v2
	v_add_f32_e32 v3, v61, v60
	v_add_f32_e32 v2, v3, v2
	v_add_f32_e32 v3, v73, v72
	v_add_f32_e32 v22, v3, v2
	global_load_dwordx4 v[2:5], v[108:109], off offset:16
	global_load_dwordx4 v[10:13], v[108:109], off
	global_load_dwordx4 v[6:9], v[110:111], off offset:16
	global_load_dwordx4 v[14:17], v[110:111], off
	global_load_dwordx4 v[228:231], v[108:109], off offset:2064
	global_load_dwordx4 v[244:247], v[108:109], off offset:2048
	global_load_dwordx4 v[232:235], v[110:111], off offset:2064
	global_load_dwordx2 v[170:171], v[110:111], off offset:2048
	global_load_dwordx2 v[236:237], v[110:111], off offset:2056
	global_load_dwordx4 v[162:165], v[116:117], off
	global_load_dwordx2 v[242:243], v[112:113], off
	global_load_dwordx2 v[80:81], v[112:113], off offset:8
	global_load_dwordx4 v[86:89], v[114:115], off
	global_load_dwordx4 v[90:93], v[118:119], off
	global_load_dwordx4 v[252:255], v[124:125], off
	global_load_dwordx2 v[180:181], v[120:121], off
	global_load_dwordx2 v[206:207], v[120:121], off offset:8
	global_load_dwordx4 v[166:169], v[122:123], off
	global_load_dwordx4 v[248:251], v[126:127], off
	ds_bpermute_b32 v21, v152, v19
	ds_bpermute_b32 v20, v152, v18
	v_add_f32_e32 v26, v35, v34
	v_add_f32_e32 v0, v26, v0
	v_lshlrev_b32_e32 v26, 16, v27
	v_and_b32_e32 v27, 0xffff0000, v27
	s_waitcnt lgkmcnt(0)
; DI unsigned pk2(float a, float b) { f32x2 v = {a, b}; bf16v2 r = __builtin_convertvector(v, bf16v2); return __builtin_bit_cast(unsigned, r); }
; DI unsigned pkh2(float a, float b) { f32x2 v = {a, b}; h16v2 r = __builtin_convertvector(v, h16v2); return __builtin_bit_cast(unsigned, r); }
; DI float shflx(float v, int mask, int lane) { return __int_as_float(__builtin_amdgcn_ds_bpermute((lane ^ mask) << 2, __float_as_int(v))); }
; DI void phase_ln(const Params& p, int layer, int gw, int NGW, int lane) {
;     ...
; #pragma unroll
;         for (int o = 1; o < 64; o <<= 1)
; #pragma unroll
;             for (int q = 0; q < R; ++q) { s1[q] += shflx(s1[q], o, lane); s2[q] += shflx(s2[q], o, lane); }
;         float mean[R], rstd[R];
; #pragma unroll
;         for (int q = 0; q < R; ++q) { mean[q] = s1[q] * (1.f / D); const float var = fmaxf(s2[q] * (1.f / D) - mean[q] * mean[q], 0.f); rstd[q] = 1.0f / sqrtf(var + LN_EPS); }
; #pragma unroll
;         for (int j = 0; j < 4; ++j) {
;             const f32x4 g0 = ((const f32x4*)g)[128 * j + 2 * lane], g1 = ((const f32x4*)g)[128 * j + 2 * lane + 1], b0 = ((const f32x4*)b)[128 * j + 2 * lane], b1 = ((const f32x4*)b)[128 * j + 2 * lane + 1];
;             const float gg[8] = {g0[0], g0[1], g0[2], g0[3], g1[0], g1[1], g1[2], g1[3]}, bb[8] = {b0[0], b0[1], b0[2], b0[3], b1[0], b1[1], b1[2], b1[3]};
; #pragma unroll
;             for (int q = 0; q < R; ++q) { if (!ok[q]) continue;
;                 float y[8];
; #pragma unroll
;                 for (int e = 0; e < 8; ++e) y[e] = (v[q][8 * j + e] - mean[q]) * rstd[q] * gg[e] + bb[e];
;                 if (last) { f32x4* o = (f32x4*)(p.out + (size_t)rr[q] * D) + 128 * j + 2 * lane; o[0] = (f32x4){y[0], y[1], y[2], y[3]}; o[1] = (f32x4){y[4], y[5], y[6], y[7]}; }
;                 else { u32x4 hw; hw.x = pkh2(y[0], y[1]); hw.y = pkh2(y[2], y[3]); hw.z = pkh2(y[4], y[5]); hw.w = pkh2(y[6], y[7]);
;                        ((u32x4*)(h16out + (size_t)rr[q] * D) + lane)[64 * j] = hw;
;                        u32x4 w; w.x = pk2(y[0], y[1]); w.y = pk2(y[2], y[3]); w.z = pk2(y[4], y[5]); w.w = pk2(y[6], y[7]);
;                        ((u32x4*)(hb + (size_t)rr[q] * D) + lane)[64 * j] = w; } }
	v_pk_add_f32 v[18:19], v[18:19], v[20:21]
	ds_bpermute_b32 v21, v153, v19
	ds_bpermute_b32 v20, v153, v18
	v_pk_fma_f32 v[26:27], v[76:77], s[98:99], v[26:27] op_sel_hi:[1,0,1]
	v_and_b32_e32 v37, 0xffff0000, v28
	v_add_f32_e32 v36, v27, v26
	v_add_f32_e32 v0, v36, v0
	s_waitcnt lgkmcnt(0)
	v_pk_add_f32 v[18:19], v[18:19], v[20:21]
	ds_bpermute_b32 v21, v158, v19
	ds_bpermute_b32 v20, v158, v18
	v_lshlrev_b32_e32 v36, 16, v28
	v_pk_fma_f32 v[36:37], v[66:67], s[98:99], v[36:37] op_sel_hi:[1,0,1]
	v_pk_mul_f32 v[74:75], v[26:27], v[26:27]
	v_add_f32_e32 v28, v36, v37
	v_add_f32_e32 v0, v28, v0
	v_lshlrev_b32_e32 v28, 16, v29
	v_and_b32_e32 v29, 0xffff0000, v29
	s_waitcnt lgkmcnt(0)
	v_pk_add_f32 v[18:19], v[18:19], v[20:21]
	v_pk_fma_f32 v[28:29], v[68:69], s[98:99], v[28:29] op_sel_hi:[1,0,1]
	ds_bpermute_b32 v21, v159, v19
	ds_bpermute_b32 v20, v159, v18
	v_pk_mul_f32 v[66:67], v[36:37], v[36:37]
	v_add_f32_e32 v68, v28, v29
	v_add_f32_e32 v23, v75, v74
	v_add_f32_e32 v0, v68, v0
	v_pk_mul_f32 v[68:69], v[28:29], v[28:29]
	v_add_f32_e32 v22, v23, v22
	v_add_f32_e32 v23, v66, v67
	v_add_f32_e32 v22, v23, v22
	v_add_f32_e32 v23, v68, v69
	v_add_f32_e32 v22, v23, v22
	ds_bpermute_b32 v23, v152, v22
	s_waitcnt lgkmcnt(1)
	v_pk_add_f32 v[18:19], v[18:19], v[20:21]
	ds_bpermute_b32 v21, v160, v19
	ds_bpermute_b32 v20, v160, v18
	ds_bpermute_b32 v24, v152, v0
	s_waitcnt lgkmcnt(3)
	v_add_f32_e32 v22, v22, v23
	ds_bpermute_b32 v23, v153, v22
	v_lshl_add_u64 v[68:69], s[52:53], 0, v[98:99]
	s_waitcnt lgkmcnt(2)
	v_pk_add_f32 v[18:19], v[18:19], v[20:21]
	ds_bpermute_b32 v21, v161, v19
	ds_bpermute_b32 v20, v161, v18
	s_waitcnt lgkmcnt(2)
	v_add_f32_e32 v22, v22, v23
	ds_bpermute_b32 v23, v158, v22
	v_add_f32_e32 v0, v0, v24
	ds_bpermute_b32 v24, v153, v0
	s_waitcnt lgkmcnt(2)
	v_pk_add_f32 v[18:19], v[18:19], v[20:21]
	s_waitcnt lgkmcnt(1)
	v_add_f32_e32 v22, v22, v23
	v_pk_mul_f32 v[60:61], v[18:19], s[2:3] op_sel_hi:[1,0]
	ds_bpermute_b32 v23, v159, v22
	v_fma_f32 v18, -v61, v61, v60
	v_max_f32_e32 v18, 0, v18
	v_add_f32_e32 v18, 0x3727c5ac, v18
	v_mul_f32_e32 v19, 0x4f800000, v18
	v_cmp_gt_f32_e32 vcc, s19, v18
	s_waitcnt lgkmcnt(1)
	v_add_f32_e32 v0, v0, v24
	s_waitcnt lgkmcnt(0)
	v_add_f32_e32 v20, v22, v23
	v_cndmask_b32_e32 v18, v18, v19, vcc
	v_sqrt_f32_e32 v19, v18
	ds_bpermute_b32 v24, v158, v0
	ds_bpermute_b32 v21, v160, v20
	v_add_u32_e32 v22, -1, v19
	v_fma_f32 v23, -v22, v19, v18
	v_cmp_ge_f32_e64 s[36:37], 0, v23
	v_add_u32_e32 v23, 1, v19
	s_waitcnt lgkmcnt(1)
	v_add_f32_e32 v0, v0, v24
	v_cndmask_b32_e64 v22, v19, v22, s[36:37]
	v_fma_f32 v19, -v23, v19, v18
	v_cmp_lt_f32_e64 s[36:37], 0, v19
	ds_bpermute_b32 v24, v159, v0
	s_waitcnt lgkmcnt(1)
	v_add_f32_e32 v67, v20, v21
	v_cndmask_b32_e64 v19, v22, v23, s[36:37]
	v_mul_f32_e32 v22, 0x37800000, v19
	v_cndmask_b32_e32 v19, v19, v22, vcc
	v_cmp_class_f32_e32 vcc, v18, v174
	s_waitcnt lgkmcnt(0)
	v_add_f32_e32 v0, v0, v24
	ds_bpermute_b32 v24, v160, v0
	v_cndmask_b32_e32 v18, v19, v18, vcc
	v_div_scale_f32 v19, s[6:7], v18, v18, 1.0
	v_rcp_f32_e32 v22, v19
	s_waitcnt lgkmcnt(0)
	v_add_f32_e32 v0, v0, v24
	ds_bpermute_b32 v72, v161, v0
	ds_bpermute_b32 v73, v161, v67
	v_fma_f32 v20, -v19, v22, 1.0
	v_fmac_f32_e32 v22, v20, v22
	v_div_scale_f32 v20, vcc, 1.0, v18, 1.0
	v_mul_f32_e32 v21, v20, v22
	v_fma_f32 v23, -v19, v21, v20
	v_fmac_f32_e32 v21, v23, v22
	v_fma_f32 v19, -v19, v21, v20
	v_div_fmas_f32 v19, v19, v22, v21
	v_div_fixup_f32 v66, v19, v18, 1.0
	v_pk_add_f32 v[18:19], v[144:145], v[60:61] op_sel:[0,1] neg_lo:[0,1] neg_hi:[0,1]
	v_pk_add_f32 v[20:21], v[148:149], v[60:61] op_sel:[0,1] neg_lo:[0,1] neg_hi:[0,1]
	v_pk_add_f32 v[22:23], v[146:147], v[60:61] op_sel:[0,1] neg_lo:[0,1] neg_hi:[0,1]
	v_pk_add_f32 v[24:25], v[150:151], v[60:61] op_sel:[0,1] neg_lo:[0,1] neg_hi:[0,1]
	v_pk_mul_f32 v[18:19], v[18:19], v[66:67] op_sel_hi:[1,0]
	v_pk_mul_f32 v[20:21], v[20:21], v[66:67] op_sel_hi:[1,0]
	v_pk_mul_f32 v[22:23], v[22:23], v[66:67] op_sel_hi:[1,0]
	v_pk_mul_f32 v[24:25], v[24:25], v[66:67] op_sel_hi:[1,0]
	s_waitcnt vmcnt(0)
	v_pk_fma_f32 v[18:19], v[10:11], v[18:19], v[14:15]
	v_pk_fma_f32 v[20:21], v[12:13], v[20:21], v[16:17]
	v_pk_fma_f32 v[22:23], v[2:3], v[22:23], v[6:7]
	v_pk_fma_f32 v[24:25], v[4:5], v[24:25], v[8:9]
	s_mov_b64 s[6:7], -1
	s_and_b64 vcc, exec, s[0:1]
	s_cbranch_vccz .LBB0_365
	s_mov_b64 s[6:7], 0x8400000
	v_cvt_pk_f16_f32 v74, v18, v19
	v_cvt_pk_f16_f32 v75, v20, v21
	v_cvt_pk_f16_f32 v76, v22, v23
	v_cvt_pk_f16_f32 v77, v24, v25
	v_lshl_add_u64 v[78:79], v[132:133], 0, s[6:7]
	global_store_dwordx4 v[68:69], v[74:77], off
	s_mov_b64 s[6:7], 0
	s_nop 0
	v_cvt_pk_bf16_f32 v74, v18, v19
	v_cvt_pk_bf16_f32 v75, v20, v21
	v_cvt_pk_bf16_f32 v76, v22, v23
	v_cvt_pk_bf16_f32 v77, v24, v25
	global_store_dwordx4 v[78:79], v[74:77], off

; DI void phase_ln(const Params& p, int layer, int gw, int NGW, int lane) {
;     ...
;         for (int j = 0; j < 4; ++j) {
;             const f32x4 g0 = ((const f32x4*)g)[128 * j + 2 * lane], g1 = ((const f32x4*)g)[128 * j + 2 * lane + 1], b0 = ((const f32x4*)b)[128 * j + 2 * lane], b1 = ((const f32x4*)b)[128 * j + 2 * lane + 1];
;             const float gg[8] = {g0[0], g0[1], g0[2], g0[3], g1[0], g1[1], g1[2], g1[3]}, bb[8] = {b0[0], b0[1], b0[2], b0[3], b1[0], b1[1], b1[2], b1[3]};
; #pragma unroll
;             for (int q = 0; q < R; ++q) { if (!ok[q]) continue;
;                 float y[8];
; #pragma unroll
;                 for (int e = 0; e < 8; ++e) y[e] = (v[q][8 * j + e] - mean[q]) * rstd[q] * gg[e] + bb[e];
;                 if (last) { f32x4* o = (f32x4*)(p.out + (size_t)rr[q] * D) + 128 * j + 2 * lane; o[0] = (f32x4){y[0], y[1], y[2], y[3]}; o[1] = (f32x4){y[4], y[5], y[6], y[7]}; }
.LBB0_372:
	v_mov_b32_e32 v60, v61
	v_mov_b32_e32 v67, v66
	v_pk_add_f32 v[18:19], v[136:137], v[60:61] neg_lo:[0,1] neg_hi:[0,1]
	v_pk_add_f32 v[20:21], v[138:139], v[60:61] neg_lo:[0,1] neg_hi:[0,1]
	v_pk_add_f32 v[22:23], v[140:141], v[60:61] neg_lo:[0,1] neg_hi:[0,1]
	v_pk_add_f32 v[24:25], v[142:143], v[60:61] neg_lo:[0,1] neg_hi:[0,1]
	v_pk_mul_f32 v[18:19], v[18:19], v[66:67]
	v_pk_mul_f32 v[20:21], v[20:21], v[66:67]
	v_pk_mul_f32 v[22:23], v[22:23], v[66:67]
	v_pk_mul_f32 v[24:25], v[24:25], v[66:67]
	v_cndmask_b32_e64 v73, 0, 1, s[0:1]
	s_mov_b64 s[4:5], -1
	v_cmp_ne_u32_e64 s[38:39], 1, v73
	s_andn2_b64 vcc, exec, s[0:1]
	v_pk_fma_f32 v[22:23], v[22:23], v[228:229], v[232:233]
	v_pk_fma_f32 v[18:19], v[18:19], v[244:245], v[170:171]
	v_pk_fma_f32 v[20:21], v[20:21], v[246:247], v[236:237]
	v_pk_fma_f32 v[24:25], v[24:25], v[230:231], v[234:235]
	s_cbranch_vccz .LBB0_375
	s_andn2_b64 vcc, exec, s[4:5]
	s_cbranch_vccz .LBB0_376

; DI unsigned pk2(float a, float b) { f32x2 v = {a, b}; bf16v2 r = __builtin_convertvector(v, bf16v2); return __builtin_bit_cast(unsigned, r); }
; DI unsigned pkh2(float a, float b) { f32x2 v = {a, b}; h16v2 r = __builtin_convertvector(v, h16v2); return __builtin_bit_cast(unsigned, r); }
; DI void phase_ln(const Params& p, int layer, int gw, int NGW, int lane) {
;     ...
;         for (int j = 0; j < 4; ++j) {
;             const f32x4 g0 = ((const f32x4*)g)[128 * j + 2 * lane], g1 = ((const f32x4*)g)[128 * j + 2 * lane + 1], b0 = ((const f32x4*)b)[128 * j + 2 * lane], b1 = ((const f32x4*)b)[128 * j + 2 * lane + 1];
;             const float gg[8] = {g0[0], g0[1], g0[2], g0[3], g1[0], g1[1], g1[2], g1[3]}, bb[8] = {b0[0], b0[1], b0[2], b0[3], b1[0], b1[1], b1[2], b1[3]};
; #pragma unroll
;             for (int q = 0; q < R; ++q) { if (!ok[q]) continue;
;                 float y[8];
; #pragma unroll
;                 for (int e = 0; e < 8; ++e) y[e] = (v[q][8 * j + e] - mean[q]) * rstd[q] * gg[e] + bb[e];
;                 if (last) { f32x4* o = (f32x4*)(p.out + (size_t)rr[q] * D) + 128 * j + 2 * lane; o[0] = (f32x4){y[0], y[1], y[2], y[3]}; o[1] = (f32x4){y[4], y[5], y[6], y[7]}; }
;                 else { u32x4 hw; hw.x = pkh2(y[0], y[1]); hw.y = pkh2(y[2], y[3]); hw.z = pkh2(y[4], y[5]); hw.w = pkh2(y[6], y[7]);
;                        ((u32x4*)(h16out + (size_t)rr[q] * D) + lane)[64 * j] = hw;
;                        u32x4 w; w.x = pk2(y[0], y[1]); w.y = pk2(y[2], y[3]); w.z = pk2(y[4], y[5]); w.w = pk2(y[6], y[7]);
;                        ((u32x4*)(hb + (size_t)rr[q] * D) + lane)[64 * j] = w; } }
.LBB0_377:
	v_pk_add_f32 v[18:19], v[58:59], v[0:1] op_sel_hi:[1,0] neg_lo:[0,1] neg_hi:[0,1]
	s_and_b64 vcc, exec, s[38:39]
	v_pk_mul_f32 v[18:19], v[18:19], v[72:73] op_sel_hi:[1,0]
	s_mov_b64 s[4:5], -1
	v_pk_fma_f32 v[244:245], v[18:19], v[244:245], v[170:171]
	v_pk_add_f32 v[170:171], v[62:63], v[0:1] op_sel_hi:[1,0] neg_lo:[0,1] neg_hi:[0,1]
	s_nop 0
	v_pk_mul_f32 v[170:171], v[170:171], v[72:73] op_sel_hi:[1,0]
	s_nop 0
	v_pk_fma_f32 v[246:247], v[170:171], v[246:247], v[236:237]
	v_pk_add_f32 v[170:171], v[64:65], v[0:1] op_sel_hi:[1,0] neg_lo:[0,1] neg_hi:[0,1]
	s_nop 0
	v_pk_mul_f32 v[170:171], v[170:171], v[72:73] op_sel_hi:[1,0]
	s_nop 0
	v_pk_fma_f32 v[228:229], v[170:171], v[228:229], v[232:233]
	v_pk_add_f32 v[232:233], v[70:71], v[0:1] op_sel_hi:[1,0] neg_lo:[0,1] neg_hi:[0,1]
	s_nop 0
	v_pk_mul_f32 v[232:233], v[232:233], v[72:73] op_sel_hi:[1,0]
	s_nop 0
	v_pk_fma_f32 v[230:231], v[232:233], v[230:231], v[234:235]
	s_cbranch_vccnz .LBB0_379
	v_cvt_pk_f16_f32 v232, v244, v245
	v_cvt_pk_f16_f32 v233, v246, v247
	v_cvt_pk_f16_f32 v234, v228, v229
	v_cvt_pk_f16_f32 v235, v230, v231
	v_lshl_add_u64 v[170:171], v[106:107], 0, s[58:59]
	global_store_dwordx4 v[170:171], v[232:235], off offset:1024
	s_mov_b64 s[4:5], 0
	s_nop 0
	v_cvt_pk_bf16_f32 v232, v244, v245
	v_cvt_pk_bf16_f32 v233, v246, v247
	v_cvt_pk_bf16_f32 v234, v228, v229
	v_cvt_pk_bf16_f32 v235, v230, v231
	global_store_dwordx4 v[134:135], v[232:235], off offset:1024
.LBB0_379:
	s_andn2_b64 vcc, exec, s[4:5]
	s_cbranch_vccnz .LBB0_381
	s_lshl_b64 s[4:5], s[56:57], 13
	v_lshl_add_u64 v[232:233], v[128:129], 0, s[4:5]
	global_store_dwordx4 v[232:233], v[244:247], off offset:2048
	global_store_dwordx4 v[232:233], v[228:231], off offset:2064
.LBB0_381:
	v_pk_add_f32 v[18:19], v[46:47], v[60:61] neg_lo:[0,1] neg_hi:[0,1]
	v_pk_add_f32 v[20:21], v[50:51], v[60:61] neg_lo:[0,1] neg_hi:[0,1]
	v_pk_add_f32 v[22:23], v[48:49], v[60:61] neg_lo:[0,1] neg_hi:[0,1]
	v_pk_add_f32 v[24:25], v[52:53], v[60:61] neg_lo:[0,1] neg_hi:[0,1]
	v_pk_mul_f32 v[18:19], v[18:19], v[66:67]
	v_pk_mul_f32 v[20:21], v[20:21], v[66:67]
	v_pk_mul_f32 v[46:47], v[22:23], v[66:67]
	v_pk_mul_f32 v[48:49], v[24:25], v[66:67]
	s_and_b64 vcc, exec, s[38:39]
	s_mov_b64 s[4:5], -1
	v_pk_fma_f32 v[22:23], v[18:19], v[242:243], v[162:163]
	v_pk_fma_f32 v[24:25], v[20:21], v[80:81], v[164:165]
	v_pk_fma_f32 v[18:19], v[46:47], v[86:87], v[90:91]
	v_pk_fma_f32 v[20:21], v[48:49], v[88:89], v[92:93]
	s_cbranch_vccz .LBB0_384
	s_andn2_b64 vcc, exec, s[4:5]
	s_cbranch_vccz .LBB0_385

; DI unsigned pk2(float a, float b) { f32x2 v = {a, b}; bf16v2 r = __builtin_convertvector(v, bf16v2); return __builtin_bit_cast(unsigned, r); }
; DI unsigned pkh2(float a, float b) { f32x2 v = {a, b}; h16v2 r = __builtin_convertvector(v, h16v2); return __builtin_bit_cast(unsigned, r); }
; DI void phase_ln(const Params& p, int layer, int gw, int NGW, int lane) {
;     ...
;         for (int j = 0; j < 4; ++j) {
;             const f32x4 g0 = ((const f32x4*)g)[128 * j + 2 * lane], g1 = ((const f32x4*)g)[128 * j + 2 * lane + 1], b0 = ((const f32x4*)b)[128 * j + 2 * lane], b1 = ((const f32x4*)b)[128 * j + 2 * lane + 1];
;             const float gg[8] = {g0[0], g0[1], g0[2], g0[3], g1[0], g1[1], g1[2], g1[3]}, bb[8] = {b0[0], b0[1], b0[2], b0[3], b1[0], b1[1], b1[2], b1[3]};
; #pragma unroll
;             for (int q = 0; q < R; ++q) { if (!ok[q]) continue;
;                 float y[8];
; #pragma unroll
;                 for (int e = 0; e < 8; ++e) y[e] = (v[q][8 * j + e] - mean[q]) * rstd[q] * gg[e] + bb[e];
;                 if (last) { f32x4* o = (f32x4*)(p.out + (size_t)rr[q] * D) + 128 * j + 2 * lane; o[0] = (f32x4){y[0], y[1], y[2], y[3]}; o[1] = (f32x4){y[4], y[5], y[6], y[7]}; }
;                 else { u32x4 hw; hw.x = pkh2(y[0], y[1]); hw.y = pkh2(y[2], y[3]); hw.z = pkh2(y[4], y[5]); hw.w = pkh2(y[6], y[7]);
;                        ((u32x4*)(h16out + (size_t)rr[q] * D) + lane)[64 * j] = hw;
;                        u32x4 w; w.x = pk2(y[0], y[1]); w.y = pk2(y[2], y[3]); w.z = pk2(y[4], y[5]); w.w = pk2(y[6], y[7]);
;                        ((u32x4*)(hb + (size_t)rr[q] * D) + lane)[64 * j] = w; } }
.LBB0_386:
	v_pk_add_f32 v[18:19], v[38:39], v[0:1] op_sel_hi:[1,0] neg_lo:[0,1] neg_hi:[0,1]
	s_and_b64 vcc, exec, s[38:39]
	v_pk_mul_f32 v[18:19], v[18:19], v[72:73] op_sel_hi:[1,0]
	s_mov_b64 s[4:5], -1
	v_pk_fma_f32 v[162:163], v[18:19], v[242:243], v[162:163]
	v_pk_add_f32 v[242:243], v[40:41], v[0:1] op_sel_hi:[1,0] neg_lo:[0,1] neg_hi:[0,1]
	s_nop 0
	v_pk_mul_f32 v[242:243], v[242:243], v[72:73] op_sel_hi:[1,0]
	s_nop 0
	v_pk_fma_f32 v[164:165], v[242:243], v[80:81], v[164:165]
	v_pk_add_f32 v[242:243], v[54:55], v[0:1] op_sel_hi:[1,0] neg_lo:[0,1] neg_hi:[0,1]
	s_nop 0
	v_pk_mul_f32 v[242:243], v[242:243], v[72:73] op_sel_hi:[1,0]
	s_nop 0
	v_pk_fma_f32 v[86:87], v[242:243], v[86:87], v[90:91]
	v_pk_add_f32 v[90:91], v[56:57], v[0:1] op_sel_hi:[1,0] neg_lo:[0,1] neg_hi:[0,1]
	s_nop 0
	v_pk_mul_f32 v[90:91], v[90:91], v[72:73] op_sel_hi:[1,0]
	s_nop 0
	v_pk_fma_f32 v[88:89], v[90:91], v[88:89], v[92:93]
	s_cbranch_vccnz .LBB0_388
	v_cvt_pk_f16_f32 v90, v162, v163
	v_cvt_pk_f16_f32 v91, v164, v165
	v_cvt_pk_f16_f32 v92, v86, v87
	v_cvt_pk_f16_f32 v93, v88, v89
	v_lshl_add_u64 v[242:243], v[106:107], 0, s[58:59]
	global_store_dwordx4 v[242:243], v[90:93], off offset:2048
	s_mov_b64 s[4:5], 0
	s_nop 0
	v_cvt_pk_bf16_f32 v90, v162, v163
	v_cvt_pk_bf16_f32 v91, v164, v165
	v_cvt_pk_bf16_f32 v92, v86, v87
	v_cvt_pk_bf16_f32 v93, v88, v89
	global_store_dwordx4 v[134:135], v[90:93], off offset:2048
.LBB0_388:
	s_andn2_b64 vcc, exec, s[4:5]
	s_cbranch_vccnz .LBB0_390
	s_lshl_b64 s[4:5], s[56:57], 13
	s_add_u32 s4, s92, s4
	s_addc_u32 s5, s93, s5
	v_lshl_add_u64 v[90:91], v[104:105], 4, s[4:5]
	v_lshl_add_u64 v[92:93], v[90:91], 0, s[64:65]
	v_add_co_u32_e32 v90, vcc, 0x1000, v90
	s_nop 1
	v_addc_co_u32_e32 v91, vcc, 0, v91, vcc
	global_store_dwordx4 v[90:91], v[162:165], off
	global_store_dwordx4 v[92:93], v[86:89], off offset:16
.LBB0_390:
	v_pk_add_f32 v[18:19], v[30:31], v[60:61] neg_lo:[0,1] neg_hi:[0,1]
	v_pk_add_f32 v[20:21], v[42:43], v[60:61] neg_lo:[0,1] neg_hi:[0,1]
	v_pk_add_f32 v[22:23], v[32:33], v[60:61] neg_lo:[0,1] neg_hi:[0,1]
	v_pk_add_f32 v[24:25], v[44:45], v[60:61] neg_lo:[0,1] neg_hi:[0,1]
	v_pk_mul_f32 v[18:19], v[18:19], v[66:67]
	v_pk_mul_f32 v[20:21], v[20:21], v[66:67]
	v_pk_mul_f32 v[30:31], v[22:23], v[66:67]
	v_pk_mul_f32 v[32:33], v[24:25], v[66:67]
	s_and_b64 vcc, exec, s[38:39]
	s_mov_b64 s[4:5], -1
	v_pk_fma_f32 v[22:23], v[18:19], v[180:181], v[252:253]
	v_pk_fma_f32 v[24:25], v[20:21], v[206:207], v[254:255]
	v_pk_fma_f32 v[18:19], v[30:31], v[166:167], v[248:249]
	v_pk_fma_f32 v[20:21], v[32:33], v[168:169], v[250:251]
	s_cbranch_vccz .LBB0_393
	s_andn2_b64 vcc, exec, s[4:5]
	s_cbranch_vccz .LBB0_394

; DI unsigned pk2(float a, float b) { f32x2 v = {a, b}; bf16v2 r = __builtin_convertvector(v, bf16v2); return __builtin_bit_cast(unsigned, r); }
; DI unsigned pkh2(float a, float b) { f32x2 v = {a, b}; h16v2 r = __builtin_convertvector(v, h16v2); return __builtin_bit_cast(unsigned, r); }
; DI void phase_ln(const Params& p, int layer, int gw, int NGW, int lane) {
;     ...
;         for (int j = 0; j < 4; ++j) {
;             const f32x4 g0 = ((const f32x4*)g)[128 * j + 2 * lane], g1 = ((const f32x4*)g)[128 * j + 2 * lane + 1], b0 = ((const f32x4*)b)[128 * j + 2 * lane], b1 = ((const f32x4*)b)[128 * j + 2 * lane + 1];
;             const float gg[8] = {g0[0], g0[1], g0[2], g0[3], g1[0], g1[1], g1[2], g1[3]}, bb[8] = {b0[0], b0[1], b0[2], b0[3], b1[0], b1[1], b1[2], b1[3]};
; #pragma unroll
;             for (int q = 0; q < R; ++q) { if (!ok[q]) continue;
;                 float y[8];
; #pragma unroll
;                 for (int e = 0; e < 8; ++e) y[e] = (v[q][8 * j + e] - mean[q]) * rstd[q] * gg[e] + bb[e];
;                 if (last) { f32x4* o = (f32x4*)(p.out + (size_t)rr[q] * D) + 128 * j + 2 * lane; o[0] = (f32x4){y[0], y[1], y[2], y[3]}; o[1] = (f32x4){y[4], y[5], y[6], y[7]}; }
;                 else { u32x4 hw; hw.x = pkh2(y[0], y[1]); hw.y = pkh2(y[2], y[3]); hw.z = pkh2(y[4], y[5]); hw.w = pkh2(y[6], y[7]);
;                        ((u32x4*)(h16out + (size_t)rr[q] * D) + lane)[64 * j] = hw;
;                        u32x4 w; w.x = pk2(y[0], y[1]); w.y = pk2(y[2], y[3]); w.z = pk2(y[4], y[5]); w.w = pk2(y[6], y[7]);
;                        ((u32x4*)(hb + (size_t)rr[q] * D) + lane)[64 * j] = w; } }
.LBB0_395:
	v_pk_add_f32 v[18:19], v[34:35], v[0:1] op_sel_hi:[1,0] neg_lo:[0,1] neg_hi:[0,1]
	s_and_b64 vcc, exec, s[38:39]
	v_pk_mul_f32 v[18:19], v[18:19], v[72:73] op_sel_hi:[1,0]
	s_mov_b64 s[4:5], -1
	v_pk_fma_f32 v[252:253], v[18:19], v[180:181], v[252:253]
	v_pk_add_f32 v[180:181], v[26:27], v[0:1] op_sel_hi:[1,0] neg_lo:[0,1] neg_hi:[0,1]
	s_nop 0
	v_pk_mul_f32 v[180:181], v[180:181], v[72:73] op_sel_hi:[1,0]
	s_nop 0
	v_pk_fma_f32 v[254:255], v[180:181], v[206:207], v[254:255]
	v_pk_add_f32 v[180:181], v[36:37], v[0:1] op_sel_hi:[1,0] neg_lo:[0,1] neg_hi:[0,1]
	s_nop 0
	v_pk_mul_f32 v[180:181], v[180:181], v[72:73] op_sel_hi:[1,0]
	s_nop 0
	v_pk_fma_f32 v[166:167], v[180:181], v[166:167], v[248:249]
	v_pk_add_f32 v[248:249], v[28:29], v[0:1] op_sel_hi:[1,0] neg_lo:[0,1] neg_hi:[0,1]
	s_nop 0
	v_pk_mul_f32 v[248:249], v[248:249], v[72:73] op_sel_hi:[1,0]
	s_nop 0
	v_pk_fma_f32 v[168:169], v[248:249], v[168:169], v[250:251]
	s_cbranch_vccnz .LBB0_397
	v_cvt_pk_f16_f32 v248, v252, v253
	v_cvt_pk_f16_f32 v249, v254, v255
	v_cvt_pk_f16_f32 v250, v166, v167
	v_cvt_pk_f16_f32 v251, v168, v169
	v_lshl_add_u64 v[180:181], v[106:107], 0, s[58:59]
	global_store_dwordx4 v[180:181], v[248:251], off offset:3072
	s_mov_b64 s[4:5], 0
	s_nop 0
	v_cvt_pk_bf16_f32 v248, v252, v253
	v_cvt_pk_bf16_f32 v249, v254, v255
	v_cvt_pk_bf16_f32 v250, v166, v167
	v_cvt_pk_bf16_f32 v251, v168, v169
	global_store_dwordx4 v[134:135], v[248:251], off offset:3072
.LBB0_397:
	s_andn2_b64 vcc, exec, s[4:5]
	s_cbranch_vccnz .LBB0_356
	s_lshl_b64 s[4:5], s[56:57], 13
	s_add_u32 s4, s92, s4
	s_addc_u32 s5, s93, s5
	v_lshl_add_u64 v[248:249], v[104:105], 4, s[4:5]
	v_lshl_add_u64 v[250:251], v[248:249], 0, s[68:69]
	v_add_co_u32_e32 v248, vcc, 0x1000, v248
	s_nop 1
	v_addc_co_u32_e32 v249, vcc, 0, v249, vcc
	global_store_dwordx4 v[248:249], v[252:255], off offset:2048
	global_store_dwordx4 v[250:251], v[166:169], off offset:16
	s_branch .LBB0_356

; __global__ void __launch_bounds__(NTHREADS) hybrid_fwd(Params p) {
	.amdhsa_kernel _Z10hybrid_fwd6Params
		.amdhsa_group_segment_fixed_size 0
		.amdhsa_private_segment_fixed_size 0
		.amdhsa_kernarg_size 360
		.amdhsa_user_sgpr_count 2
		.amdhsa_user_sgpr_dispatch_ptr 0
		.amdhsa_user_sgpr_queue_ptr 0
		.amdhsa_user_sgpr_kernarg_segment_ptr 1
		.amdhsa_user_sgpr_dispatch_id 0
		.amdhsa_user_sgpr_kernarg_preload_length 0
		.amdhsa_user_sgpr_kernarg_preload_offset 0
		.amdhsa_user_sgpr_private_segment_size 0
		.amdhsa_uses_dynamic_stack 0
		.amdhsa_enable_private_segment 0
		.amdhsa_system_sgpr_workgroup_id_x 1
		.amdhsa_system_sgpr_workgroup_id_y 0
		.amdhsa_system_sgpr_workgroup_id_z 0
		.amdhsa_system_sgpr_workgroup_info 0
		.amdhsa_system_vgpr_workitem_id 2
		.amdhsa_next_free_vgpr 256
		.amdhsa_next_free_sgpr 102
		.amdhsa_accum_offset 256
		.amdhsa_reserve_vcc 1
		.amdhsa_float_round_mode_32 0
		.amdhsa_float_round_mode_16_64 0
		.amdhsa_float_denorm_mode_32 3
		.amdhsa_float_denorm_mode_16_64 3
		.amdhsa_dx10_clamp 1
		.amdhsa_ieee_mode 1
		.amdhsa_fp16_overflow 0
		.amdhsa_tg_split 0
		.amdhsa_exception_fp_ieee_invalid_op 0
		.amdhsa_exception_fp_denorm_src 0
		.amdhsa_exception_fp_ieee_div_zero 0
		.amdhsa_exception_fp_ieee_overflow 0
		.amdhsa_exception_fp_ieee_underflow 0
		.amdhsa_exception_fp_ieee_inexact 0
		.amdhsa_exception_int_div_zero 0
	.end_amdhsa_kernel

; __global__ void __launch_bounds__(NTHREADS) hybrid_fwd(Params p) {
amdhsa.kernels:
  - .agpr_count:     0
    .args:
      - .offset:         0
        .size:           104
        .value_kind:     by_value
      - .offset:         104
        .size:           4
        .value_kind:     hidden_block_count_x
      - .offset:         108
        .size:           4
        .value_kind:     hidden_block_count_y
      - .offset:         112
        .size:           4
        .value_kind:     hidden_block_count_z
      - .offset:         116
        .size:           2
        .value_kind:     hidden_group_size_x
      - .offset:         118
        .size:           2
        .value_kind:     hidden_group_size_y
      - .offset:         120
        .size:           2
        .value_kind:     hidden_group_size_z
      - .offset:         122
        .size:           2
        .value_kind:     hidden_remainder_x
      - .offset:         124
        .size:           2
        .value_kind:     hidden_remainder_y
      - .offset:         126
        .size:           2
        .value_kind:     hidden_remainder_z
      - .offset:         144
        .size:           8
        .value_kind:     hidden_global_offset_x
      - .offset:         152
        .size:           8
        .value_kind:     hidden_global_offset_y
      - .offset:         160
        .size:           8
        .value_kind:     hidden_global_offset_z
      - .offset:         168
        .size:           2
        .value_kind:     hidden_grid_dims
      - .offset:         192
        .size:           8
        .value_kind:     hidden_multigrid_sync_arg
      - .offset:         224
        .size:           4
        .value_kind:     hidden_dynamic_lds_size
    .group_segment_fixed_size: 0
    .kernarg_segment_align: 8
    .kernarg_segment_size: 360
    .language:       OpenCL C
    .language_version:
      - 2
      - 0
    .max_flat_workgroup_size: 512
    .name:           _Z10hybrid_fwd6Params
    .private_segment_fixed_size: 0
    .sgpr_count:     108
    .sgpr_spill_count: 95
    .symbol:         _Z10hybrid_fwd6Params.kd
    .uniform_work_group_size: 1
    .uses_dynamic_stack: false
    .vgpr_count:     256
    .vgpr_spill_count: 0
    .wavefront_size: 64
